# stack of the individually-neutral edits on v30: attention back-edge rotation + Q/KV0 prefetch, P1 norm wide stores, GEMM prologue batching, hyena radix-4 LDS read batching
# speedup vs baseline: 1.0036x; 1.0036x over previous
;     const int tid = threadIdx.x, lane = tid & 63, w = __builtin_amdgcn_readfirstlane(tid >> 6), r32 = lane & 31, hi = lane >> 5;
;     constexpr int KS = 144, VS = 136, KBYTES = 64 * KS, VBYTES = 64 * VS, VOFF = 2 * KBYTES;
;     const bf16_t* QKV = (const bf16_t*)(a.ws + WS_QKV); bf16_t* OB = (bf16_t*)(a.ws + WS_OB); const float* ROPE = (const float*)(a.ws + WS_ROPE);
;     const float* qgain = a.in[10]; const float* sink = a.in[12];
;     const float C2 = 0.125f * 1.4426950408889634f;
;     const int krow = w * 8 + (lane >> 3), kch = lane & 7;
;     for (int unit = vcu; unit < 4096; unit += G) {
;         const int b = unit >> 9, kvh = (unit >> 7) & 3, qb = unit & 127, q0 = qb * 64;
;         const int head = kvh * 4 + (w & 3), qrow = q0 + 32 * (w >> 2) + r32;
;         const int jlo = (q0 < 128) ? ((128 - q0) >> 6) : 0; const int jhi = (q0 > SEQ - 192) ? ((SEQ + 64 - q0) >> 6) : 4; const int ntiles = 4 + (jhi - jlo + 1);
;         bf16x8 qr[4];
;         {
;             const bf16_t* qp = QKV + (size_t)(b * SEQ + qrow) * NQKV + head * 64;
;             float qf[4][8]; float ss = 0.f;
; #pragma unroll
;             for (int d0 = 0; d0 < 4; ++d0) { const u32x4 v = *(const u32x4*)(qp + 8 * (2 * d0 + hi));
.LBB0_499:
	s_cmp_lt_i32 s30, 5
	s_cselect_b64 s[4:5], -1, 0
	s_and_b64 s[0:1], s[4:5], s[0:1]
	s_andn2_b64 vcc, exec, s[0:1]
	s_cbranch_vccnz .LBB0_526
	s_cmpk_gt_i32 s96, 0xfff
	v_readfirstlane_b32 s8, v152
	s_cbranch_scc1 .LBB0_526
	s_add_u32 s4, s28, 0xfa00000
	s_addc_u32 s5, s29, 0
	v_and_b32_e32 v5, 31, v152
	s_movk_i32 s10, 0x90
	s_add_u32 s6, s28, 0x1c000000
	v_bfe_u32 v3, v152, 5, 1
	v_mad_u32_u24 v6, v5, s10, 0
	s_addc_u32 s7, s29, 0
	v_and_b32_e32 v1, 7, v152
	v_lshlrev_b32_e32 v0, 3, v3
	v_lshl_add_u32 v145, v3, 4, v6
	v_lshlrev_b32_e32 v4, 2, v3
	v_lshlrev_b32_e32 v3, 3, v5
	s_lshr_b32 s20, s8, 6
	v_lshlrev_b32_e32 v2, 3, v1
	v_sub_u32_e32 v3, v6, v3
	v_lshlrev_b32_e32 v6, 4, v1
	v_bfe_u32 v1, v152, 3, 3
	s_lshl_b32 s21, s20, 3
	v_or_b32_e32 v154, s21, v1
	s_bfe_u32 s11, s8, 0x20006
	s_lshr_b32 s8, s8, 3
	v_mbcnt_lo_u32_b32 v1, -1, 0
	s_and_b32 s8, s8, 0x1fffffe0
	v_mbcnt_hi_u32_b32 v1, -1, v1
	v_and_b32_e32 v144, 63, v152
	v_or_b32_e32 v175, s8, v5
	v_and_b32_e32 v5, 64, v1
	v_add_u32_e32 v174, v3, v0
	v_cmp_gt_u32_e32 vcc, 32, v144
	v_xor_b32_e32 v3, 32, v1
	v_add_u32_e32 v5, 64, v5
	s_mul_i32 s8, s20, 0x440
	v_cndmask_b32_e64 v151, 0, 1.0, vcc
	v_cmp_lt_i32_e32 vcc, v3, v5
	s_add_i32 s8, s8, 0
	v_mov_b32_e32 v147, 0
	v_and_b32_e32 v146, 32, v152
	v_cndmask_b32_e32 v1, v1, v3, vcc
	v_lshl_add_u32 v178, v144, 1, s8
	s_lshl_b32 s8, s20, 4
	s_mov_b64 s[34:35], s[66:67]
	v_readlane_b32 s52, v255, 4
	v_lshlrev_b32_e32 v176, 2, v1
	v_mul_lo_u32 v1, v154, s10
	v_lshl_add_u64 v[8:9], s[28:29], 0, v[146:147]
	s_mov_b64 s[12:13], 0x100000
	s_add_u32 s42, s4, s8
	s_mov_b32 s9, 0
	v_readlane_b32 s53, v255, 5
	v_readlane_b32 s54, v255, 6
	v_readlane_b32 s55, v255, 7
	v_readlane_b32 s56, v255, 8
	v_readlane_b32 s57, v255, 9
	v_add3_u32 v177, 0, v6, v1
	v_lshl_add_u64 v[156:157], v[8:9], 0, s[12:13]
	v_mov_b32_e32 v7, v147
	s_addc_u32 s43, s5, 0
	v_sub_u32_e32 v1, v175, v4
	v_lshlrev_b32_e32 v164, 1, v2
	s_lshl_b32 s12, s21, 1
	v_lshl_add_u64 v[148:149], s[56:57], 0, v[146:147]
	v_mov_b32_e32 v155, v147
	v_mov_b32_e32 v150, v147
	v_lshl_add_u64 v[158:159], s[4:5], 0, v[6:7]
	s_lshl_b32 s44, s96, 6
	s_lshl_b32 s45, s3, 6
	v_add_u32_e32 v179, 0x84, v1
	s_movk_i32 s46, 0xc00
	v_mov_b64_e32 v[160:161], s[4:5]
	v_lshlrev_b32_e32 v162, 1, v0
	v_mov_b32_e32 v163, v147
	v_mov_b32_e32 v180, 0x358637bd
	s_mov_b32 s47, 0x800000
	s_mov_b32 s10, 0x3e38aa3b
	s_mov_b32 s20, s12
	s_mov_b32 s21, s9
	s_mov_b32 s52, 0x41000000
	s_movk_i32 s53, 0xfefe
	s_mov_b32 s54, 0xffff
	v_lshlrev_b32_e32 v166, 1, v4
	v_mov_b32_e32 v168, v164
	v_mov_b32_e32 v169, v147
	v_mov_b32_e32 v181, 0xff800000
	s_mov_b32 s55, s96
	v_readlane_b32 s58, v255, 10
	v_readlane_b32 s59, v255, 11
	v_readlane_b32 s60, v255, 12
	v_readlane_b32 s61, v255, 13
	v_readlane_b32 s62, v255, 14
	v_readlane_b32 s63, v255, 15
	v_readlane_b32 s64, v255, 16
	v_readlane_b32 s65, v255, 17
	v_readlane_b32 s66, v255, 18
	v_readlane_b32 s67, v255, 19
	s_lshl_b32 s8, s55, 6
	s_ashr_i32 s22, s55, 9
	s_bfe_u32 s25, s55, 0x20007
	s_and_b32 s13, s8, 0x1fc0
	s_lshl_b32 s8, s25, 2
	v_add_u32_e32 v146, s13, v175
	s_lshl_b32 s24, s22, 13
	s_or_b32 s38, s8, s11
	v_add_u32_e32 v170, s24, v146
	v_mad_i64_i32 v[0:1], s[40:41], v170, s46, v[160:161]
	s_lshl_b32 s8, s38, 7
	v_lshl_add_u64 v[0:1], v[0:1], 0, s[8:9]
	v_lshl_add_u64 v[0:1], v[0:1], 0, v[162:163]
	global_load_dwordx4 v[192:195], v[0:1], off offset:32
	global_load_dwordx4 v[196:199], v[0:1], off offset:96
	global_load_dwordx4 v[200:203], v[0:1], off
	global_load_dwordx4 v[204:207], v[0:1], off offset:64
	s_lshl_b32 s39, s22, 8
	s_add_i32 s22, s39, 0x10000
	s_ashr_i32 s23, s22, 31
	v_lshl_add_u64 v[74:75], s[22:23], 0, v[154:155]
	s_lshl_b32 s8, s25, 7
	v_mad_u64_u32 v[190:191], s[40:41], v74, s46, v[160:161]
	v_mad_i32_i24 v191, v75, s46, v191
	v_lshl_add_u64 v[190:191], v[190:191], 0, s[8:9]
	v_or_b32_e32 v242, s22, v144
	v_mad_i64_i32 v[242:243], s[40:41], v242, s46, v[160:161]
	v_lshl_add_u64 v[242:243], v[242:243], 0, s[8:9]
	v_lshl_add_u64 v[190:191], v[190:191], 0, v[168:169]
	v_lshl_add_u64 v[242:243], v[242:243], 0, s[20:21]
	global_load_dwordx4 v[244:247], v[190:191], off offset:2048
	global_load_dwordx4 v[248:251], v[242:243], off offset:2560
	s_branch .LBB0_503
.LBB0_502:
	s_mul_i32 s8, s59, 0x2200
	v_add_u32_e32 v4, s8, v174
	v_add_u32_e32 v12, 0x4800, v4
	ds_read2_b64 v[0:3], v12 offset1:2
	v_bfi_b32 v135, s54, v135, v135
	v_add_u32_e32 v48, 0x5800, v4
	ds_read2_b64 v[4:7], v48 offset0:36 offset1:38
	v_bfi_b32 v131, s54, v131, v131
	ds_bpermute_b32 v52, v176, v165
	v_bfi_b32 v127, s54, v127, v127
	v_bfi_b32 v123, s54, v123, v123
	s_lshl_b32 s8, s56, 1
	s_waitcnt lgkmcnt(2)
	v_mfma_f32_32x32x16_bf16 v[16:31], v[0:3], v[132:135], v[16:31]
	ds_read2_b64 v[0:3], v48 offset0:32 offset1:34
	v_mov_b32_e32 v167, v147
	s_add_i32 s55, s55, s3
	s_add_i32 s44, s44, s45
	s_cmpk_gt_i32 s55, 0xfff
	s_waitcnt lgkmcnt(0)
	v_mfma_f32_32x32x16_bf16 v[32:47], v[0:3], v[132:135], v[32:47]
	ds_read2_b64 v[0:3], v12 offset0:4 offset1:6
	s_waitcnt lgkmcnt(0)
	v_mfma_f32_32x32x16_bf16 v[16:31], v[0:3], v[128:131], v[16:31]
	ds_read2_b64 v[0:3], v12 offset0:8 offset1:10
	ds_read2_b64 v[8:11], v48 offset0:40 offset1:42
	ds_read2_b64 v[12:15], v12 offset0:12 offset1:14
	ds_read2_b64 v[48:51], v48 offset0:44 offset1:46
	s_waitcnt lgkmcnt(0)
	s_barrier
; __device__ __forceinline__ unsigned pk2(float lo, float hi) { f32x2 v = {lo, hi}; bf16x2_t b = __builtin_convertvector(v, bf16x2_t); return __builtin_bit_cast(unsigned, b); }
;     ...
;             const bf16_t* qp = QKV + (size_t)(b * SEQ + qrow) * NQKV + head * 64;
;             float qf[4][8]; float ss = 0.f;
; #pragma unroll
;             for (int d0 = 0; d0 < 4; ++d0) { const u32x4 v = *(const u32x4*)(qp + 8 * (2 * d0 + hi));
;     ...
;         const float lt = l_run + __shfl_xor(l_run, 32); const float inv = 1.0f / lt;
;         bf16_t* op = OB + (size_t)(b * SEQ + qrow) * 1024 + head * 64 + 4 * hi;
; #pragma unroll
;         for (int g = 0; g < 4; ++g) {
;             u32x2 w0, w1; w0.x = pk2(o0[4 * g] * inv, o0[4 * g + 1] * inv); w0.y = pk2(o0[4 * g + 2] * inv, o0[4 * g + 3] * inv);
;             w1.x = pk2(o1[4 * g] * inv, o1[4 * g + 1] * inv); w1.y = pk2(o1[4 * g + 2] * inv, o1[4 * g + 3] * inv);
;             *(u32x2*)(op + 8 * g) = w0; *(u32x2*)(op + 32 + 8 * g) = w1;
;         }
	v_mfma_f32_32x32x16_bf16 v[32:47], v[4:7], v[128:131], v[32:47]
	v_add_f32_e32 v4, v165, v52
	v_div_scale_f32 v5, s[22:23], v4, v4, 1.0
	v_rcp_f32_e32 v6, v5
	v_mfma_f32_32x32x16_bf16 v[16:31], v[0:3], v[124:127], v[16:31]
	v_fma_f32 v0, -v5, v6, 1.0
	v_fmac_f32_e32 v6, v0, v6
	v_div_scale_f32 v0, vcc, 1.0, v4, 1.0
	v_mul_f32_e32 v1, v0, v6
	v_fma_f32 v2, -v5, v1, v0
	v_fmac_f32_e32 v1, v2, v6
	v_mfma_f32_32x32x16_bf16 v[32:47], v[8:11], v[124:127], v[32:47]
	v_fma_f32 v0, -v5, v1, v0
	v_div_fmas_f32 v0, v0, v6, v1
	v_div_fixup_f32 v0, v0, v4, 1.0
	v_lshlrev_b64 v[2:3], 11, v[170:171]
	v_lshl_add_u64 v[2:3], s[6:7], 0, v[2:3]
	v_lshl_add_u64 v[2:3], v[2:3], 0, s[8:9]
	v_lshl_add_u64 v[2:3], v[2:3], 0, v[166:167]
	v_mfma_f32_32x32x16_bf16 v[16:31], v[12:15], v[120:123], v[16:31]
	v_mfma_f32_32x32x16_bf16 v[32:47], v[48:51], v[120:123], v[32:47]
	s_nop 10
	v_and_b32_e32 v52, 32, v152
	v_lshrrev_b32_e32 v52, 2, v52
	v_mov_b32_e32 v53, 0
	v_lshl_add_u64 v[2:3], v[2:3], 0, v[52:53]
	v_pk_mul_f32 v[4:5], v[16:17], v[0:1] op_sel_hi:[1,0]
	v_pk_mul_f32 v[6:7], v[18:19], v[0:1] op_sel_hi:[1,0]
	v_pk_mul_f32 v[8:9], v[20:21], v[0:1] op_sel_hi:[1,0]
	v_pk_mul_f32 v[10:11], v[22:23], v[0:1] op_sel_hi:[1,0]
	v_cvt_pk_bf16_f32 v4, v4, v5
	v_cvt_pk_bf16_f32 v5, v6, v7
	v_cvt_pk_bf16_f32 v6, v8, v9
	v_cvt_pk_bf16_f32 v7, v10, v11
	v_pk_mul_f32 v[8:9], v[24:25], v[0:1] op_sel_hi:[1,0]
	v_pk_mul_f32 v[10:11], v[26:27], v[0:1] op_sel_hi:[1,0]
	v_pk_mul_f32 v[12:13], v[28:29], v[0:1] op_sel_hi:[1,0]
	v_pk_mul_f32 v[14:15], v[30:31], v[0:1] op_sel_hi:[1,0]
	v_permlane32_swap_b32 v4, v6
	v_permlane32_swap_b32 v5, v7
	global_store_dwordx4 v[2:3], v[4:7], off
	v_cvt_pk_bf16_f32 v8, v8, v9
	v_cvt_pk_bf16_f32 v9, v10, v11
	v_cvt_pk_bf16_f32 v10, v12, v13
	v_cvt_pk_bf16_f32 v11, v14, v15
	v_pk_mul_f32 v[12:13], v[32:33], v[0:1] op_sel_hi:[1,0]
	v_pk_mul_f32 v[14:15], v[34:35], v[0:1] op_sel_hi:[1,0]
	v_pk_mul_f32 v[48:49], v[36:37], v[0:1] op_sel_hi:[1,0]
	v_pk_mul_f32 v[50:51], v[38:39], v[0:1] op_sel_hi:[1,0]
	v_permlane32_swap_b32 v8, v10
	v_permlane32_swap_b32 v9, v11
	global_store_dwordx4 v[2:3], v[8:11], off offset:32
	v_cvt_pk_bf16_f32 v12, v12, v13
	v_cvt_pk_bf16_f32 v13, v14, v15
	v_cvt_pk_bf16_f32 v14, v48, v49
	v_cvt_pk_bf16_f32 v15, v50, v51
	v_pk_mul_f32 v[48:49], v[40:41], v[0:1] op_sel_hi:[1,0]
	v_pk_mul_f32 v[50:51], v[42:43], v[0:1] op_sel_hi:[1,0]
	v_pk_mul_f32 v[52:53], v[44:45], v[0:1] op_sel_hi:[1,0]
	v_pk_mul_f32 v[54:55], v[46:47], v[0:1] op_sel_hi:[1,0]
	v_permlane32_swap_b32 v12, v14
	v_permlane32_swap_b32 v13, v15
	global_store_dwordx4 v[2:3], v[12:15], off offset:64
	v_cvt_pk_bf16_f32 v48, v48, v49
	v_cvt_pk_bf16_f32 v49, v50, v51
	v_cvt_pk_bf16_f32 v50, v52, v53
	v_cvt_pk_bf16_f32 v51, v54, v55
	s_nop 1
	v_permlane32_swap_b32 v48, v50
	v_permlane32_swap_b32 v49, v51
	global_store_dwordx4 v[2:3], v[48:51], off offset:96
	s_cbranch_scc1 .Lq_skip
	s_lshl_b32 s8, s55, 6
	s_ashr_i32 s22, s55, 9
	s_bfe_u32 s25, s55, 0x20007
	s_and_b32 s13, s8, 0x1fc0
	s_lshl_b32 s8, s25, 2
	v_add_u32_e32 v146, s13, v175
	s_lshl_b32 s24, s22, 13
	s_or_b32 s38, s8, s11
	v_add_u32_e32 v170, s24, v146
	v_mad_i64_i32 v[0:1], s[40:41], v170, s46, v[160:161]
	s_lshl_b32 s8, s38, 7
	v_lshl_add_u64 v[0:1], v[0:1], 0, s[8:9]
	v_lshl_add_u64 v[0:1], v[0:1], 0, v[162:163]
	global_load_dwordx4 v[192:195], v[0:1], off offset:32
	global_load_dwordx4 v[196:199], v[0:1], off offset:96
	global_load_dwordx4 v[200:203], v[0:1], off
	global_load_dwordx4 v[204:207], v[0:1], off offset:64
	s_lshl_b32 s39, s22, 8
	s_add_i32 s22, s39, 0x10000
	s_ashr_i32 s23, s22, 31
	v_lshl_add_u64 v[74:75], s[22:23], 0, v[154:155]
	s_lshl_b32 s8, s25, 7
	v_mad_u64_u32 v[190:191], s[40:41], v74, s46, v[160:161]
	v_mad_i32_i24 v191, v75, s46, v191
	v_lshl_add_u64 v[190:191], v[190:191], 0, s[8:9]
	v_or_b32_e32 v242, s22, v144
	v_mad_i64_i32 v[242:243], s[40:41], v242, s46, v[160:161]
	v_lshl_add_u64 v[242:243], v[242:243], 0, s[8:9]
	v_lshl_add_u64 v[190:191], v[190:191], 0, v[168:169]
	v_lshl_add_u64 v[242:243], v[242:243], 0, s[20:21]
	global_load_dwordx4 v[244:247], v[190:191], off offset:2048
	global_load_dwordx4 v[248:251], v[242:243], off offset:2560
.Lq_skip:
	s_cmpk_gt_i32 s55, 0xfff
	s_cbranch_scc1 .LBB0_525
; __device__ __forceinline__ float bf_lo(unsigned w) { return __uint_as_float(w << 16); }
; __device__ __forceinline__ float bf_hi(unsigned w) { return __uint_as_float(w & 0xffff0000u); }
;     ...
;             const bf16_t* qp = QKV + (size_t)(b * SEQ + qrow) * NQKV + head * 64;
;             float qf[4][8]; float ss = 0.f;
; #pragma unroll
;             for (int d0 = 0; d0 < 4; ++d0) { const u32x4 v = *(const u32x4*)(qp + 8 * (2 * d0 + hi));
;                 qf[d0][0] = bf_lo(v.x); qf[d0][1] = bf_hi(v.x); qf[d0][2] = bf_lo(v.y); qf[d0][3] = bf_hi(v.y); qf[d0][4] = bf_lo(v.z); qf[d0][5] = bf_hi(v.z); qf[d0][6] = bf_lo(v.w); qf[d0][7] = bf_hi(v.w);
; #pragma unroll
;                 for (int i = 0; i < 8; ++i) ss += qf[d0][i] * qf[d0][i]; }
;             ss += __shfl_xor(ss, 32);
;             const float rstd = rsqrtf(ss * (1.0f / 64.0f) + 1e-6f);
; #pragma unroll
;             for (int d0 = 0; d0 < 4; ++d0)
; #pragma unroll
;                 for (int i = 0; i < 8; ++i) qf[d0][i] *= rstd * qgain[8 * (2 * d0 + hi) + i];
;             const float* rp = ROPE + (size_t)qrow * 64;
.LBB0_503:
	global_load_dwordx4 v[8:11], v[148:149], off offset:80
	global_load_dwordx4 v[12:15], v[148:149], off offset:64
	s_nop 0
	global_load_dwordx4 v[0:3], v[148:149], off offset:208
	global_load_dwordx4 v[4:7], v[148:149], off offset:192
	global_load_dwordx4 v[24:27], v[148:149], off offset:16
	global_load_dwordx4 v[36:39], v[148:149], off
	global_load_dwordx4 v[16:19], v[148:149], off offset:144
	s_waitcnt lgkmcnt(0)
	global_load_dwordx4 v[20:23], v[148:149], off offset:128
	v_lshlrev_b64 v[48:49], 8, v[146:147]
	s_lshl_b32 s8, s38, 2
	v_readlane_b32 s72, v255, 4
	v_lshl_add_u64 v[72:73], v[156:157], 0, v[48:49]
	v_mov_b32_e32 v76, s8
	v_readlane_b32 s80, v255, 12
	v_readlane_b32 s81, v255, 13
	global_load_dwordx4 v[48:51], v[72:73], off offset:64
	global_load_dwordx4 v[52:55], v[72:73], off offset:192
	global_load_dwordx4 v[56:59], v[72:73], off offset:16
	global_load_dwordx4 v[60:63], v[72:73], off
	global_load_dwordx4 v[64:67], v[72:73], off offset:144
	global_load_dwordx4 v[68:71], v[72:73], off offset:128
	global_load_dword v124, v76, s[80:81]
	s_lshl_b32 s8, s25, 7
	v_readlane_b32 s73, v255, 5
	v_readlane_b32 s74, v255, 6
	v_readlane_b32 s75, v255, 7
	v_readlane_b32 s76, v255, 8
	v_readlane_b32 s77, v255, 9
	v_readlane_b32 s78, v255, 10
	v_readlane_b32 s79, v255, 11
	v_readlane_b32 s82, v255, 14
	v_readlane_b32 s83, v255, 15
	v_readlane_b32 s84, v255, 16
	v_readlane_b32 s85, v255, 17
	v_readlane_b32 s86, v255, 18
	v_readlane_b32 s87, v255, 19
	s_waitcnt vmcnt(0)
	v_mov_b32_e32 v40, v192
	v_mov_b32_e32 v41, v193
	v_mov_b32_e32 v42, v194
	v_mov_b32_e32 v43, v195
	v_mov_b32_e32 v44, v196
	v_mov_b32_e32 v45, v197
	v_mov_b32_e32 v46, v198
	v_mov_b32_e32 v47, v199
	v_mov_b32_e32 v32, v200
	v_mov_b32_e32 v33, v201
	v_mov_b32_e32 v34, v202
	v_mov_b32_e32 v35, v203
	v_mov_b32_e32 v28, v204
	v_mov_b32_e32 v29, v205
	v_mov_b32_e32 v30, v206
	v_mov_b32_e32 v31, v207
	v_lshlrev_b32_e32 v86, 16, v40
	v_and_b32_e32 v87, 0xffff0000, v40
	v_lshlrev_b32_e32 v100, 16, v32
	v_and_b32_e32 v101, 0xffff0000, v32
	v_lshlrev_b32_e32 v96, 16, v33
	v_and_b32_e32 v97, 0xffff0000, v33
	v_pk_mul_f32 v[120:121], v[100:101], v[100:101]
	v_pk_mul_f32 v[116:117], v[96:97], v[96:97]
	v_add_f32_e32 v120, v120, v121
	v_lshlrev_b32_e32 v92, 16, v34
	v_and_b32_e32 v93, 0xffff0000, v34
	v_add_f32_e32 v116, v116, v120
	v_pk_mul_f32 v[112:113], v[92:93], v[92:93]
	v_add_f32_e32 v116, v117, v116
	v_lshlrev_b32_e32 v88, 16, v35
	v_and_b32_e32 v89, 0xffff0000, v35
	v_add_f32_e32 v112, v112, v116
	v_pk_mul_f32 v[108:109], v[88:89], v[88:89]
	v_add_f32_e32 v112, v113, v112
	v_add_f32_e32 v108, v108, v112
	v_pk_mul_f32 v[104:105], v[86:87], v[86:87]
	v_add_f32_e32 v108, v109, v108
	v_lshlrev_b32_e32 v78, 16, v47
	v_and_b32_e32 v79, 0xffff0000, v47
	v_lshlrev_b32_e32 v82, 16, v46
	v_and_b32_e32 v83, 0xffff0000, v46
	v_lshlrev_b32_e32 v46, 16, v41
	v_and_b32_e32 v47, 0xffff0000, v41
	v_add_f32_e32 v104, v104, v108
	v_lshlrev_b32_e32 v76, 16, v43
	v_and_b32_e32 v77, 0xffff0000, v43
	v_lshlrev_b32_e32 v80, 16, v42
	v_and_b32_e32 v81, 0xffff0000, v42
	v_pk_mul_f32 v[42:43], v[46:47], v[46:47]
	v_add_f32_e32 v104, v105, v104
	v_add_f32_e32 v42, v42, v104
	v_pk_mul_f32 v[32:33], v[80:81], v[80:81]
	v_add_f32_e32 v42, v43, v42
	v_add_f32_e32 v32, v32, v42
	v_lshlrev_b32_e32 v98, 16, v29
	v_and_b32_e32 v99, 0xffff0000, v29
	v_lshlrev_b32_e32 v102, 16, v28
	v_and_b32_e32 v103, 0xffff0000, v28
	v_pk_mul_f32 v[28:29], v[76:77], v[76:77]
	v_add_f32_e32 v32, v33, v32
	v_add_f32_e32 v28, v28, v32
	v_pk_mul_f32 v[122:123], v[102:103], v[102:103]
	v_add_f32_e32 v28, v29, v28
	v_add_f32_e32 v28, v122, v28
	v_pk_mul_f32 v[118:119], v[98:99], v[98:99]
	v_add_f32_e32 v28, v123, v28
	v_lshlrev_b32_e32 v94, 16, v30
	v_and_b32_e32 v95, 0xffff0000, v30
	v_add_f32_e32 v28, v118, v28
	v_pk_mul_f32 v[114:115], v[94:95], v[94:95]
	v_add_f32_e32 v28, v119, v28
	v_lshlrev_b32_e32 v90, 16, v31
	v_and_b32_e32 v91, 0xffff0000, v31
	v_add_f32_e32 v28, v114, v28
	v_pk_mul_f32 v[110:111], v[90:91], v[90:91]
	v_add_f32_e32 v28, v115, v28
	v_lshlrev_b32_e32 v40, 16, v44
	v_and_b32_e32 v41, 0xffff0000, v44
	v_add_f32_e32 v28, v110, v28
	v_pk_mul_f32 v[106:107], v[40:41], v[40:41]
	v_add_f32_e32 v28, v111, v28
	v_lshlrev_b32_e32 v84, 16, v45
	v_and_b32_e32 v85, 0xffff0000, v45
	v_add_f32_e32 v28, v106, v28
	v_pk_mul_f32 v[44:45], v[84:85], v[84:85]
	v_add_f32_e32 v28, v107, v28
	v_add_f32_e32 v28, v44, v28
	v_pk_mul_f32 v[34:35], v[82:83], v[82:83]
	v_add_f32_e32 v28, v45, v28
	v_add_f32_e32 v28, v34, v28
	v_pk_mul_f32 v[30:31], v[78:79], v[78:79]
	v_add_f32_e32 v28, v35, v28
	v_add_f32_e32 v28, v30, v28
	v_add_f32_e32 v30, v31, v28
	ds_bpermute_b32 v31, v176, v30
	s_waitcnt lgkmcnt(0)
; __device__ __forceinline__ unsigned pk2(float lo, float hi) { f32x2 v = {lo, hi}; bf16x2_t b = __builtin_convertvector(v, bf16x2_t); return __builtin_bit_cast(unsigned, b); }
; #define LOAD_TILE(ti, kreg, vreg) do { const int k0_ = TILE_K0(ti); const size_t grow_ = ((ti) < 4) ? (size_t)(M_ + b * LCTX + k0_) : (size_t)(b * SEQ + k0_); \
;         kreg = *(const u32x4*)(QKV + (grow_ + krow) * NQKV + 1024 + kvh * 64 + 8 * kch); vreg = *(const u32x4*)(QKV + (grow_ + lane) * NQKV + 1280 + kvh * 64 + 8 * w); } while (0)
; #define LOAD_TILE(ti, kreg, vreg) do { const int k0_ = TILE_K0(ti); const size_t grow_ = ((ti) < 4) ? (size_t)(M_ + b * LCTX + k0_) : (size_t)(b * SEQ + k0_); \
;         kreg = *(const u32x4*)(QKV + (grow_ + krow) * NQKV + 1024 + kvh * 64 + 8 * kch); vreg = *(const u32x4*)(QKV + (grow_ + lane) * NQKV + 1280 + kvh * 64 + 8 * w); } while (0)
;     ...
;             const float rstd = rsqrtf(ss * (1.0f / 64.0f) + 1e-6f);
; #pragma unroll
;             for (int d0 = 0; d0 < 4; ++d0)
; #pragma unroll
;                 for (int i = 0; i < 8; ++i) qf[d0][i] *= rstd * qgain[8 * (2 * d0 + hi) + i];
;             const float* rp = ROPE + (size_t)qrow * 64;
;             float qo[4][8];
; #pragma unroll
;             for (int d0 = 0; d0 < 2; ++d0)
; #pragma unroll
;                 for (int i = 0; i < 8; ++i) { const int j = 8 * (2 * d0 + hi) + i; const float cs = rp[j], sn = rp[32 + j];
;                     qo[d0][i] = qf[d0][i] * cs - qf[d0 + 2][i] * sn; qo[d0 + 2][i] = qf[d0][i] * sn + qf[d0 + 2][i] * cs; }
; #pragma unroll
;             for (int d0 = 0; d0 < 4; ++d0) { u32x4 pw; pw.x = pk2(qo[d0][0] * C2, qo[d0][1] * C2); pw.y = pk2(qo[d0][2] * C2, qo[d0][3] * C2); pw.z = pk2(qo[d0][4] * C2, qo[d0][5] * C2); pw.w = pk2(qo[d0][6] * C2, qo[d0][7] * C2);
;                 qr[d0] = __builtin_bit_cast(bf16x8, pw); }
;         }
;         float m_ref = sink[head] * 1.4426950408889634f; float l_run = hi ? 0.f : 1.f;
;         f32x16 o0 = {}, o1 = {}; f32x16 negm;
; #pragma unroll
;         for (int r = 0; r < 16; ++r) negm[r] = -m_ref;
;         u32x4 kreg, vreg, kreg2, vreg2, kreg3, vreg3;
;     ...
;         LOAD_TILE(0, kreg, vreg); STORE_TILE(0, 0); LOAD_TILE(1, kreg, vreg); LOAD_TILE(2, kreg2, vreg2); LOAD_TILE(3, kreg3, vreg3); __syncthreads();
	v_add_f32_e32 v30, v30, v31
	v_fmamk_f32 v42, v30, 0x3c800000, v180
	v_mul_f32_e32 v43, 0x4b800000, v42
	v_cmp_gt_f32_e32 vcc, s47, v42
	s_add_i32 s22, s39, 0x10040
	s_ashr_i32 s23, s22, 31
	v_cndmask_b32_e32 v42, v42, v43, vcc
	v_rsq_f32_e32 v104, v42
	global_load_dwordx4 v[42:45], v[72:73], off offset:80
	s_nop 0
	global_load_dwordx4 v[72:75], v[72:73], off offset:208
	v_mul_f32_e32 v146, 0x3fb8aa3b, v124
	ds_write_b128 v177, v[244:247]
	ds_write_b16 v178, v248 offset:18432
	ds_write_b16_d16_hi v178, v248 offset:18568
	ds_write_b16 v178, v249 offset:18704
	ds_write_b16_d16_hi v178, v249 offset:18840
	ds_write_b16 v178, v250 offset:18976
	ds_write_b16_d16_hi v178, v250 offset:19112
	ds_write_b16 v178, v251 offset:19248
	ds_write_b16_d16_hi v178, v251 offset:19384
	v_mul_f32_e32 v105, 0x45800000, v104
	v_cndmask_b32_e32 v104, v104, v105, vcc
	v_pk_mul_f32 v[36:37], v[36:37], v[104:105] op_sel_hi:[1,0]
	v_pk_mul_f32 v[8:9], v[8:9], v[104:105] op_sel_hi:[1,0]
	v_pk_mul_f32 v[36:37], v[36:37], v[100:101]
	v_pk_mul_f32 v[100:101], v[8:9], v[80:81]
	v_pk_mul_f32 v[8:9], v[10:11], v[104:105] op_sel_hi:[1,0]
	v_pk_mul_f32 v[0:1], v[0:1], v[104:105] op_sel_hi:[1,0]
	v_pk_mul_f32 v[76:77], v[8:9], v[76:77]
	v_pk_mul_f32 v[8:9], v[20:21], v[104:105] op_sel_hi:[1,0]
	v_pk_mul_f32 v[38:39], v[38:39], v[104:105] op_sel_hi:[1,0]
	v_pk_mul_f32 v[12:13], v[12:13], v[104:105] op_sel_hi:[1,0]
	v_pk_mul_f32 v[8:9], v[8:9], v[102:103]
	v_pk_mul_f32 v[10:11], v[22:23], v[104:105] op_sel_hi:[1,0]
	v_pk_mul_f32 v[112:113], v[0:1], v[82:83]
	v_pk_mul_f32 v[0:1], v[2:3], v[104:105] op_sel_hi:[1,0]
	v_pk_mul_f32 v[38:39], v[38:39], v[96:97]
	v_pk_mul_f32 v[24:25], v[24:25], v[104:105] op_sel_hi:[1,0]
	v_pk_mul_f32 v[96:97], v[12:13], v[86:87]
	v_pk_mul_f32 v[12:13], v[14:15], v[104:105] op_sel_hi:[1,0]
	v_pk_mul_f32 v[10:11], v[10:11], v[98:99]
	v_pk_mul_f32 v[78:79], v[0:1], v[78:79]
	v_pk_mul_f32 v[0:1], v[60:61], v[8:9]
	v_pk_mul_f32 v[24:25], v[24:25], v[92:93]
	v_pk_mul_f32 v[26:27], v[26:27], v[104:105] op_sel_hi:[1,0]
	v_pk_mul_f32 v[46:47], v[12:13], v[46:47]
	v_pk_mul_f32 v[12:13], v[16:17], v[104:105] op_sel_hi:[1,0]
	v_pk_fma_f32 v[114:115], v[68:69], v[36:37], v[0:1]
	v_pk_mul_f32 v[0:1], v[62:63], v[10:11]
	v_pk_mul_f32 v[26:27], v[26:27], v[88:89]
	v_pk_mul_f32 v[12:13], v[12:13], v[94:95]
	v_pk_mul_f32 v[14:15], v[18:19], v[104:105] op_sel_hi:[1,0]
	v_pk_fma_f32 v[116:117], v[70:71], v[38:39], v[0:1]
	v_pk_mul_f32 v[0:1], v[64:65], v[24:25]
	v_pk_mul_f32 v[14:15], v[14:15], v[90:91]
	v_pk_fma_f32 v[118:119], v[56:57], v[12:13], v[0:1]
	v_pk_mul_f32 v[0:1], v[26:27], v[66:67]
	v_pk_mul_f32 v[4:5], v[4:5], v[104:105] op_sel_hi:[1,0]
	v_pk_fma_f32 v[120:121], v[14:15], v[58:59], v[0:1]
	v_pk_mul_f32 v[0:1], v[68:69], v[8:9]
	v_pk_mul_f32 v[98:99], v[4:5], v[40:41]
	v_pk_fma_f32 v[0:1], v[60:61], v[36:37], v[0:1] neg_lo:[0,0,1] neg_hi:[0,0,1]
	v_pk_mul_f32 v[4:5], v[6:7], v[104:105] op_sel_hi:[1,0]
	v_pk_mul_f32 v[0:1], v[0:1], s[10:11] op_sel_hi:[1,0]
	v_pk_mul_f32 v[102:103], v[4:5], v[84:85]
	v_cvt_pk_bf16_f32 v80, v0, v1
	v_pk_mul_f32 v[0:1], v[70:71], v[10:11]
	v_lshl_add_u64 v[10:11], s[22:23], 0, v[154:155]
	v_pk_fma_f32 v[0:1], v[62:63], v[38:39], v[0:1] neg_lo:[0,0,1] neg_hi:[0,0,1]
	v_pk_mul_f32 v[16:17], v[102:103], v[54:55]
	v_pk_mul_f32 v[0:1], v[0:1], s[10:11] op_sel_hi:[1,0]
	v_pk_fma_f32 v[16:17], v[46:47], v[50:51], v[16:17] neg_lo:[0,0,1] neg_hi:[0,0,1]
	v_cvt_pk_bf16_f32 v81, v0, v1
	v_pk_mul_f32 v[0:1], v[12:13], v[64:65]
	v_mad_u64_u32 v[12:13], s[40:41], v10, s46, v[160:161]
	v_mad_i32_i24 v13, v11, s46, v13
	v_lshl_add_u64 v[10:11], v[12:13], 0, s[8:9]
	v_or_b32_e32 v12, s22, v144
	v_mad_i64_i32 v[12:13], s[22:23], v12, s46, v[160:161]
	s_add_i32 s22, s39, 0x10080
	v_lshl_add_u64 v[10:11], v[10:11], 0, v[168:169]
	v_lshl_add_u64 v[12:13], v[12:13], 0, s[8:9]
	s_ashr_i32 s23, s22, 31
	v_lshl_add_u64 v[12:13], v[12:13], 0, s[20:21]
	global_load_dwordx4 v[38:41], v[10:11], off offset:2048
	global_load_dwordx4 v[34:37], v[12:13], off offset:2560
	v_lshl_add_u64 v[10:11], s[22:23], 0, v[154:155]
	v_mad_u64_u32 v[12:13], s[40:41], v10, s46, v[160:161]
	v_mad_i32_i24 v13, v11, s46, v13
	v_lshl_add_u64 v[10:11], v[12:13], 0, s[8:9]
	v_or_b32_e32 v12, s22, v144
	v_mad_i64_i32 v[12:13], s[22:23], v12, s46, v[160:161]
	s_add_i32 s22, s39, 0x100c0
	v_lshl_add_u64 v[10:11], v[10:11], 0, v[168:169]
	v_lshl_add_u64 v[12:13], v[12:13], 0, s[8:9]
	s_ashr_i32 s23, s22, 31
	v_lshl_add_u64 v[12:13], v[12:13], 0, s[20:21]
	global_load_dwordx4 v[108:111], v[10:11], off offset:2048
	global_load_dwordx4 v[104:107], v[12:13], off offset:2560
	v_lshl_add_u64 v[10:11], s[22:23], 0, v[154:155]
	v_mad_u64_u32 v[12:13], s[40:41], v10, s46, v[160:161]
	v_mad_i32_i24 v13, v11, s46, v13
	v_lshl_add_u64 v[10:11], v[12:13], 0, s[8:9]
	v_or_b32_e32 v12, s22, v144
	v_mad_i64_i32 v[12:13], s[22:23], v12, s46, v[160:161]
	v_lshl_add_u64 v[10:11], v[10:11], 0, v[168:169]
	v_lshl_add_u64 v[12:13], v[12:13], 0, s[8:9]
	v_pk_fma_f32 v[0:1], v[24:25], v[56:57], v[0:1] neg_lo:[0,0,1] neg_hi:[0,0,1]
	v_lshl_add_u64 v[12:13], v[12:13], 0, s[20:21]
	global_load_dwordx4 v[88:91], v[10:11], off offset:2048
	global_load_dwordx4 v[92:95], v[12:13], off offset:2560
	v_pk_mul_f32 v[0:1], v[0:1], s[10:11] op_sel_hi:[1,0]
	s_waitcnt lgkmcnt(0)
	v_cvt_pk_bf16_f32 v82, v0, v1
	v_pk_mul_f32 v[0:1], v[14:15], v[66:67]
	s_barrier
; __device__ __forceinline__ unsigned pk2(float lo, float hi) { f32x2 v = {lo, hi}; bf16x2_t b = __builtin_convertvector(v, bf16x2_t); return __builtin_bit_cast(unsigned, b); }
;     ...
; #pragma unroll
;             for (int d0 = 0; d0 < 4; ++d0) { u32x4 pw; pw.x = pk2(qo[d0][0] * C2, qo[d0][1] * C2); pw.y = pk2(qo[d0][2] * C2, qo[d0][3] * C2); pw.z = pk2(qo[d0][4] * C2, qo[d0][5] * C2); pw.w = pk2(qo[d0][6] * C2, qo[d0][7] * C2);
;                 qr[d0] = __builtin_bit_cast(bf16x8, pw); }
;         }
;         float m_ref = sink[head] * 1.4426950408889634f; float l_run = hi ? 0.f : 1.f;
;         f32x16 o0 = {}, o1 = {}; f32x16 negm;
; #pragma unroll
;         for (int r = 0; r < 16; ++r) negm[r] = -m_ref;
;         u32x4 kreg, vreg, kreg2, vreg2, kreg3, vreg3;
	v_pk_fma_f32 v[0:1], v[26:27], v[58:59], v[0:1] neg_lo:[0,0,1] neg_hi:[0,0,1]
	ds_read_b128 v[56:59], v145
	v_pk_mul_f32 v[0:1], v[0:1], s[10:11] op_sel_hi:[1,0]
	ds_read_b128 v[60:63], v145 offset:4608
	ds_read_b128 v[64:67], v145 offset:32
	v_cvt_pk_bf16_f32 v83, v0, v1
	v_pk_mul_f32 v[0:1], v[98:99], v[52:53]
	v_pk_mul_f32 v[16:17], v[16:17], s[10:11] op_sel_hi:[1,0]
	v_pk_fma_f32 v[0:1], v[96:97], v[48:49], v[0:1] neg_lo:[0,0,1] neg_hi:[0,0,1]
	v_cvt_pk_bf16_f32 v85, v16, v17
	v_pk_mul_f32 v[0:1], v[0:1], s[10:11] op_sel_hi:[1,0]
	s_waitcnt vmcnt(6)
	v_pk_mul_f32 v[68:69], v[112:113], v[72:73]
	v_cvt_pk_bf16_f32 v84, v0, v1
	v_xor_b32_e32 v0, 0x80000000, v146
	v_mov_b32_e32 v1, v0
	v_mov_b32_e32 v2, v0
	v_mov_b32_e32 v3, v0
	v_mov_b32_e32 v4, v0
	v_mov_b32_e32 v5, v0
	v_mov_b32_e32 v6, v0
	v_mov_b32_e32 v7, v0
	v_mov_b32_e32 v8, v0
	v_mov_b32_e32 v9, v0
	v_mov_b32_e32 v10, v0
	v_mov_b32_e32 v11, v0
	v_mov_b32_e32 v12, v0
	v_mov_b32_e32 v13, v0
	v_mov_b32_e32 v14, v0
	v_mov_b32_e32 v15, v0
	v_pk_mul_f32 v[52:53], v[96:97], v[52:53]
	s_waitcnt lgkmcnt(2)
	v_mfma_f32_32x32x16_bf16 v[18:33], v[56:59], v[80:83], v[0:15]
	v_mov_b64_e32 v[16:17], v[14:15]
	ds_read_b128 v[56:59], v145 offset:4640
	s_nop 4
	v_mov_b64_e32 v[14:15], v[12:13]
	v_mov_b64_e32 v[12:13], v[10:11]
	v_mov_b64_e32 v[10:11], v[8:9]
	v_mov_b64_e32 v[8:9], v[6:7]
	v_mov_b64_e32 v[6:7], v[4:5]
	v_mov_b64_e32 v[4:5], v[2:3]
	v_mov_b64_e32 v[2:3], v[0:1]
	s_waitcnt lgkmcnt(2)
	s_nop 0
	v_mfma_f32_32x32x16_bf16 v[2:17], v[60:63], v[80:83], v[2:17]
	v_fma_f32 v60, v100, v42, -v68
	v_fma_f32 v61, v101, v43, -v69
	v_mul_f32_e64 v62, v46, v54
	v_mul_f32_e64 v63, v47, v55
	v_mul_f32_e64 v60, v60, s10
	v_mul_f32_e64 v61, v61, s10
	v_pk_mul_f32 v[46:47], v[114:115], s[10:11] op_sel_hi:[1,0]
	v_cvt_pk_bf16_f32 v86, v60, v61
	v_pk_mul_f32 v[60:61], v[78:79], v[74:75]
	v_cvt_pk_bf16_f32 v96, v46, v47
	v_pk_fma_f32 v[60:61], v[76:77], v[44:45], v[60:61] neg_lo:[0,0,1] neg_hi:[0,0,1]
	s_nop 0
	v_pk_mul_f32 v[60:61], v[60:61], s[10:11] op_sel_hi:[1,0]
	s_nop 0
	v_cvt_pk_bf16_f32 v87, v60, v61
	v_pk_fma_f32 v[60:61], v[98:99], v[48:49], v[52:53]
	ds_read_b128 v[46:49], v145 offset:64
	s_waitcnt lgkmcnt(2)
	v_mfma_f32_32x32x16_bf16 v[18:33], v[64:67], v[84:87], v[18:33]
	v_mul_f32_e64 v52, v116, s10
	v_mul_f32_e64 v53, v117, s10
	v_mul_f32_e64 v60, v60, s10
	v_mul_f32_e64 v61, v61, s10
	v_cvt_pk_bf16_f32 v97, v52, v53
	v_pk_mul_f32 v[52:53], v[118:119], s[10:11] op_sel_hi:[1,0]
	s_nop 0
	v_cvt_pk_bf16_f32 v98, v52, v53
	v_pk_mul_f32 v[52:53], v[120:121], s[10:11] op_sel_hi:[1,0]
	s_waitcnt lgkmcnt(1)
	v_mfma_f32_32x32x16_bf16 v[2:17], v[56:59], v[84:87], v[2:17]
	v_cvt_pk_bf16_f32 v99, v52, v53
	ds_read_b128 v[52:55], v145 offset:4672
	ds_read_b128 v[56:59], v145 offset:96
	s_waitcnt lgkmcnt(2)
	v_mfma_f32_32x32x16_bf16 v[18:33], v[46:49], v[96:99], v[18:33]
	v_mul_f32_e64 v48, v100, v72
	v_mul_f32_e64 v49, v101, v73
	v_fma_f32 v46, v102, v50, v62
	v_fma_f32 v47, v103, v51, v63
	v_fma_f32 v48, v112, v42, v48
	v_fma_f32 v49, v113, v43, v49
	v_pk_mul_f32 v[42:43], v[76:77], v[74:75]
	v_pk_mul_f32 v[46:47], v[46:47], s[10:11] op_sel_hi:[1,0]
	v_pk_fma_f32 v[50:51], v[78:79], v[44:45], v[42:43]
	ds_read_b128 v[42:45], v145 offset:4704
	s_waitcnt lgkmcnt(2)
	v_mfma_f32_32x32x16_bf16 v[2:17], v[52:55], v[96:99], v[2:17]
	v_cvt_pk_bf16_f32 v101, v46, v47
	v_mul_f32_e64 v46, v48, s10
	v_mul_f32_e64 v47, v49, s10
	v_cvt_pk_bf16_f32 v100, v60, v61
	v_cvt_pk_bf16_f32 v102, v46, v47
	v_pk_mul_f32 v[46:47], v[50:51], s[10:11] op_sel_hi:[1,0]
	s_nop 0
	v_cvt_pk_bf16_f32 v103, v46, v47
	s_waitcnt lgkmcnt(1)
	s_nop 0
	v_mfma_f32_32x32x16_bf16 v[18:33], v[56:59], v[100:103], v[18:33]
	s_waitcnt lgkmcnt(0)
	v_mfma_f32_32x32x16_bf16 v[2:17], v[42:45], v[100:103], v[2:17]
	s_nop 9
	v_max_f32_e32 v42, v19, v19
	v_max_f32_e32 v43, v20, v20
	v_max_f32_e32 v44, v21, v21
	v_max_f32_e32 v1, v3, v3
	v_max_f32_e32 v1, v42, v1
	v_max_f32_e32 v42, v4, v4
	v_max_f32_e32 v42, v43, v42
	v_max_f32_e32 v43, v5, v5
	v_max3_f32 v1, v18, v2, v1
	v_max_f32_e32 v43, v44, v43
	v_max3_f32 v1, v1, v42, v43
	v_max_f32_e32 v42, v6, v6
	v_max_f32_e32 v43, v22, v22
	v_max_f32_e32 v42, v43, v42
	v_max_f32_e32 v43, v7, v7
	v_max_f32_e32 v44, v23, v23
	v_max_f32_e32 v43, v44, v43
	v_max3_f32 v1, v1, v42, v43
	v_max_f32_e32 v42, v8, v8
	v_max_f32_e32 v43, v24, v24
	v_max_f32_e32 v42, v43, v42
	v_max_f32_e32 v43, v9, v9
	v_max_f32_e32 v44, v25, v25
	v_max_f32_e32 v43, v44, v43
	v_max3_f32 v1, v1, v42, v43
	v_max_f32_e32 v42, v10, v10
	v_max_f32_e32 v43, v26, v26
	v_max_f32_e32 v42, v43, v42
	v_max_f32_e32 v43, v11, v11
	v_max_f32_e32 v44, v27, v27
	v_max_f32_e32 v43, v44, v43
	v_max3_f32 v1, v1, v42, v43
	v_max_f32_e32 v42, v12, v12
	v_max_f32_e32 v43, v28, v28
	v_max_f32_e32 v42, v43, v42
	v_max_f32_e32 v43, v13, v13
	v_max_f32_e32 v44, v29, v29
	v_max_f32_e32 v43, v44, v43
	v_max3_f32 v1, v1, v42, v43
	v_max_f32_e32 v42, v14, v14
	v_max_f32_e32 v43, v30, v30
	v_max_f32_e32 v42, v43, v42
	v_max_f32_e32 v43, v15, v15
	v_max_f32_e32 v44, v31, v31
	v_max_f32_e32 v43, v44, v43
	v_max3_f32 v1, v1, v42, v43
	v_max_f32_e32 v42, v16, v16
	v_max_f32_e32 v43, v32, v32
	v_max_f32_e32 v42, v43, v42
	v_max_f32_e32 v43, v17, v17
	v_max_f32_e32 v44, v33, v33
	v_max_f32_e32 v43, v44, v43
	v_max3_f32 v1, v1, v42, v43
	ds_bpermute_b32 v42, v176, v1
	s_waitcnt lgkmcnt(0)
	v_max_f32_e32 v42, v42, v42
	v_max_f32_e32 v1, v1, v42
	v_cmp_lt_f32_e32 vcc, s52, v1
	s_cmp_eq_u64 vcc, 0
	s_cselect_b64 s[22:23], -1, 0
	s_cbranch_vccz .LBB0_505
	v_max_f32_e32 v0, v1, v1
	v_max_f32_e32 v42, 0, v0
	v_exp_f32_e64 v44, -v42
	v_add_f32_e32 v146, v146, v42
	v_xor_b32_e32 v0, 0x80000000, v146
	v_pk_add_f32 v[18:19], v[18:19], v[42:43] op_sel_hi:[1,0] neg_lo:[0,1] neg_hi:[0,1]
	v_pk_add_f32 v[2:3], v[2:3], v[42:43] op_sel_hi:[1,0] neg_lo:[0,1] neg_hi:[0,1]
	v_pk_add_f32 v[20:21], v[20:21], v[42:43] op_sel_hi:[1,0] neg_lo:[0,1] neg_hi:[0,1]
	v_pk_add_f32 v[4:5], v[4:5], v[42:43] op_sel_hi:[1,0] neg_lo:[0,1] neg_hi:[0,1]
	v_pk_add_f32 v[22:23], v[22:23], v[42:43] op_sel_hi:[1,0] neg_lo:[0,1] neg_hi:[0,1]
	v_pk_add_f32 v[6:7], v[6:7], v[42:43] op_sel_hi:[1,0] neg_lo:[0,1] neg_hi:[0,1]
	v_pk_add_f32 v[24:25], v[24:25], v[42:43] op_sel_hi:[1,0] neg_lo:[0,1] neg_hi:[0,1]
	v_pk_add_f32 v[8:9], v[8:9], v[42:43] op_sel_hi:[1,0] neg_lo:[0,1] neg_hi:[0,1]
	v_pk_add_f32 v[26:27], v[26:27], v[42:43] op_sel_hi:[1,0] neg_lo:[0,1] neg_hi:[0,1]
	v_pk_add_f32 v[10:11], v[10:11], v[42:43] op_sel_hi:[1,0] neg_lo:[0,1] neg_hi:[0,1]
	v_pk_add_f32 v[28:29], v[28:29], v[42:43] op_sel_hi:[1,0] neg_lo:[0,1] neg_hi:[0,1]
	v_pk_add_f32 v[12:13], v[12:13], v[42:43] op_sel_hi:[1,0] neg_lo:[0,1] neg_hi:[0,1]
	v_pk_add_f32 v[30:31], v[30:31], v[42:43] op_sel_hi:[1,0] neg_lo:[0,1] neg_hi:[0,1]
	v_pk_add_f32 v[14:15], v[14:15], v[42:43] op_sel_hi:[1,0] neg_lo:[0,1] neg_hi:[0,1]
	v_pk_add_f32 v[32:33], v[32:33], v[42:43] op_sel_hi:[1,0] neg_lo:[0,1] neg_hi:[0,1]
	v_pk_add_f32 v[16:17], v[16:17], v[42:43] op_sel_hi:[1,0] neg_lo:[0,1] neg_hi:[0,1]
	v_pk_mul_f32 v[42:43], v[150:151], v[44:45] op_sel_hi:[1,0]
	s_branch .LBB0_506

; #define LAS __attribute__((address_space(3)))
; template <bool INV> __device__ __forceinline__ void fft_pass4(LAS cf* z, int tid) {
; #pragma unroll 2
;     for (int it = 0; it < 8; ++it) {
;         const int g = tid + 512 * it; const int pb = PH(4 * g);
;         f32x4 v0 = *(LAS f32x4*)(z + pb), v1 = *(LAS f32x4*)(z + pb + 2);
;         cf a0 = {v0[0], v0[1]}, a1 = {v0[2], v0[3]}, a2 = {v1[0], v1[1]}, a3 = {v1[2], v1[3]};
;         dft4<INV>(a0, a1, a2, a3);
;         *(LAS f32x4*)(z + pb) = (f32x4){a0.x, a0.y, a1.x, a1.y}; *(LAS f32x4*)(z + pb + 2) = (f32x4){a2.x, a2.y, a3.x, a3.y};
;     }
;     __syncthreads();
; }
; __device__ __forceinline__ void hyena_phase(LAS unsigned char* L, const Args& a, int vcu, int G) {
;     ...
;         fft_pass4<false>(z, tid);
.LBB0_1030:
	v_mov_b32_e32 v22, v160
	v_xor_b32_e32 v22, v22, v176
	v_lshl_add_u32 v182, v22, 3, 0
	v_add_u32_e32 v22, 0x800, v160
	v_xor_b32_e32 v22, v22, v176
	v_lshl_add_u32 v183, v22, 3, 0
	v_add_u32_e32 v22, 0x1000, v160
	v_xor_b32_e32 v22, v22, v176
	v_lshl_add_u32 v216, v22, 3, 0
	v_add_u32_e32 v22, 0x1800, v160
	v_xor_b32_e32 v22, v22, v176
	v_lshl_add_u32 v217, v22, 3, 0
	v_add_u32_e32 v22, 0x2000, v160
	v_xor_b32_e32 v22, v22, v176
	v_lshl_add_u32 v226, v22, 3, 0
	v_add_u32_e32 v22, 0x2800, v160
	v_xor_b32_e32 v22, v22, v176
	v_lshl_add_u32 v227, v22, 3, 0
	v_add_u32_e32 v22, 0x3000, v160
	v_xor_b32_e32 v22, v22, v176
	v_lshl_add_u32 v41, v22, 3, 0
	v_add_u32_e32 v22, 0x3800, v160
	v_xor_b32_e32 v22, v22, v176
	v_lshl_add_u32 v125, v22, 3, 0
	ds_read_b128 v[112:115], v182
	ds_read_b128 v[230:233], v182 offset:16
	ds_read_b128 v[240:243], v183
	ds_read_b128 v[244:247], v183 offset:16
	s_waitcnt lgkmcnt(2)
	v_pk_add_f32 v[22:23], v[112:113], v[230:231]
	v_pk_add_f32 v[38:39], v[114:115], v[232:233]
	v_pk_add_f32 v[30:31], v[112:113], v[230:231] neg_lo:[0,1] neg_hi:[0,1]
	v_pk_add_f32 v[42:43], v[114:115], v[232:233] neg_lo:[0,1] neg_hi:[0,1]
	v_pk_add_f32 v[112:113], v[22:23], v[38:39]
	v_pk_add_f32 v[114:115], v[30:31], v[42:43] op_sel:[0,1] op_sel_hi:[1,0] neg_hi:[0,1]
	v_pk_add_f32 v[230:231], v[22:23], v[38:39] neg_lo:[0,1] neg_hi:[0,1]
	v_pk_add_f32 v[232:233], v[30:31], v[42:43] op_sel:[0,1] op_sel_hi:[1,0] neg_lo:[0,1]
	ds_write_b128 v182, v[112:115]
	ds_write_b128 v182, v[230:233] offset:16
	s_waitcnt lgkmcnt(2)
	v_pk_add_f32 v[22:23], v[240:241], v[244:245]
	v_pk_add_f32 v[38:39], v[242:243], v[246:247]
	v_pk_add_f32 v[30:31], v[240:241], v[244:245] neg_lo:[0,1] neg_hi:[0,1]
	v_pk_add_f32 v[42:43], v[242:243], v[246:247] neg_lo:[0,1] neg_hi:[0,1]
	v_pk_add_f32 v[240:241], v[22:23], v[38:39]
	v_pk_add_f32 v[242:243], v[30:31], v[42:43] op_sel:[0,1] op_sel_hi:[1,0] neg_hi:[0,1]
	v_pk_add_f32 v[244:245], v[22:23], v[38:39] neg_lo:[0,1] neg_hi:[0,1]
	v_pk_add_f32 v[246:247], v[30:31], v[42:43] op_sel:[0,1] op_sel_hi:[1,0] neg_lo:[0,1]
	ds_write_b128 v183, v[240:243]
	ds_write_b128 v183, v[244:247] offset:16
	ds_read_b128 v[112:115], v216
	ds_read_b128 v[230:233], v216 offset:16
	ds_read_b128 v[240:243], v217
	ds_read_b128 v[244:247], v217 offset:16
	s_waitcnt lgkmcnt(2)
	v_pk_add_f32 v[22:23], v[112:113], v[230:231]
	v_pk_add_f32 v[38:39], v[114:115], v[232:233]
	v_pk_add_f32 v[30:31], v[112:113], v[230:231] neg_lo:[0,1] neg_hi:[0,1]
	v_pk_add_f32 v[42:43], v[114:115], v[232:233] neg_lo:[0,1] neg_hi:[0,1]
	v_pk_add_f32 v[112:113], v[22:23], v[38:39]
	v_pk_add_f32 v[114:115], v[30:31], v[42:43] op_sel:[0,1] op_sel_hi:[1,0] neg_hi:[0,1]
	v_pk_add_f32 v[230:231], v[22:23], v[38:39] neg_lo:[0,1] neg_hi:[0,1]
	v_pk_add_f32 v[232:233], v[30:31], v[42:43] op_sel:[0,1] op_sel_hi:[1,0] neg_lo:[0,1]
	ds_write_b128 v216, v[112:115]
	ds_write_b128 v216, v[230:233] offset:16
	s_waitcnt lgkmcnt(2)
	v_pk_add_f32 v[22:23], v[240:241], v[244:245]
	v_pk_add_f32 v[38:39], v[242:243], v[246:247]
	v_pk_add_f32 v[30:31], v[240:241], v[244:245] neg_lo:[0,1] neg_hi:[0,1]
	v_pk_add_f32 v[42:43], v[242:243], v[246:247] neg_lo:[0,1] neg_hi:[0,1]
	v_pk_add_f32 v[240:241], v[22:23], v[38:39]
	v_pk_add_f32 v[242:243], v[30:31], v[42:43] op_sel:[0,1] op_sel_hi:[1,0] neg_hi:[0,1]
	v_pk_add_f32 v[244:245], v[22:23], v[38:39] neg_lo:[0,1] neg_hi:[0,1]
	v_pk_add_f32 v[246:247], v[30:31], v[42:43] op_sel:[0,1] op_sel_hi:[1,0] neg_lo:[0,1]
	ds_write_b128 v217, v[240:243]
	ds_write_b128 v217, v[244:247] offset:16
	ds_read_b128 v[112:115], v226
	ds_read_b128 v[230:233], v226 offset:16
	ds_read_b128 v[240:243], v227
	ds_read_b128 v[244:247], v227 offset:16
	s_waitcnt lgkmcnt(2)
	v_pk_add_f32 v[22:23], v[112:113], v[230:231]
	v_pk_add_f32 v[38:39], v[114:115], v[232:233]
	v_pk_add_f32 v[30:31], v[112:113], v[230:231] neg_lo:[0,1] neg_hi:[0,1]
	v_pk_add_f32 v[42:43], v[114:115], v[232:233] neg_lo:[0,1] neg_hi:[0,1]
	v_pk_add_f32 v[112:113], v[22:23], v[38:39]
	v_pk_add_f32 v[114:115], v[30:31], v[42:43] op_sel:[0,1] op_sel_hi:[1,0] neg_hi:[0,1]
	v_pk_add_f32 v[230:231], v[22:23], v[38:39] neg_lo:[0,1] neg_hi:[0,1]
	v_pk_add_f32 v[232:233], v[30:31], v[42:43] op_sel:[0,1] op_sel_hi:[1,0] neg_lo:[0,1]
	ds_write_b128 v226, v[112:115]
	ds_write_b128 v226, v[230:233] offset:16
	s_waitcnt lgkmcnt(2)
	v_pk_add_f32 v[22:23], v[240:241], v[244:245]
	v_pk_add_f32 v[38:39], v[242:243], v[246:247]
	v_pk_add_f32 v[30:31], v[240:241], v[244:245] neg_lo:[0,1] neg_hi:[0,1]
	v_pk_add_f32 v[42:43], v[242:243], v[246:247] neg_lo:[0,1] neg_hi:[0,1]
	v_pk_add_f32 v[240:241], v[22:23], v[38:39]
	v_pk_add_f32 v[242:243], v[30:31], v[42:43] op_sel:[0,1] op_sel_hi:[1,0] neg_hi:[0,1]
	v_pk_add_f32 v[244:245], v[22:23], v[38:39] neg_lo:[0,1] neg_hi:[0,1]
	v_pk_add_f32 v[246:247], v[30:31], v[42:43] op_sel:[0,1] op_sel_hi:[1,0] neg_lo:[0,1]
	ds_write_b128 v227, v[240:243]
	ds_write_b128 v227, v[244:247] offset:16
	ds_read_b128 v[112:115], v41
	ds_read_b128 v[230:233], v41 offset:16
	ds_read_b128 v[240:243], v125
	ds_read_b128 v[244:247], v125 offset:16
	s_waitcnt lgkmcnt(2)
	v_pk_add_f32 v[22:23], v[112:113], v[230:231]
	v_pk_add_f32 v[38:39], v[114:115], v[232:233]
	v_pk_add_f32 v[30:31], v[112:113], v[230:231] neg_lo:[0,1] neg_hi:[0,1]
	v_pk_add_f32 v[42:43], v[114:115], v[232:233] neg_lo:[0,1] neg_hi:[0,1]
	v_pk_add_f32 v[112:113], v[22:23], v[38:39]
	v_pk_add_f32 v[114:115], v[30:31], v[42:43] op_sel:[0,1] op_sel_hi:[1,0] neg_hi:[0,1]
	v_pk_add_f32 v[230:231], v[22:23], v[38:39] neg_lo:[0,1] neg_hi:[0,1]
	v_pk_add_f32 v[232:233], v[30:31], v[42:43] op_sel:[0,1] op_sel_hi:[1,0] neg_lo:[0,1]
	ds_write_b128 v41, v[112:115]
	ds_write_b128 v41, v[230:233] offset:16
	s_waitcnt lgkmcnt(2)
	v_pk_add_f32 v[22:23], v[240:241], v[244:245]
	v_pk_add_f32 v[38:39], v[242:243], v[246:247]
	v_pk_add_f32 v[30:31], v[240:241], v[244:245] neg_lo:[0,1] neg_hi:[0,1]
	v_pk_add_f32 v[42:43], v[242:243], v[246:247] neg_lo:[0,1] neg_hi:[0,1]
	v_pk_add_f32 v[240:241], v[22:23], v[38:39]
	v_pk_add_f32 v[242:243], v[30:31], v[42:43] op_sel:[0,1] op_sel_hi:[1,0] neg_hi:[0,1]
	v_pk_add_f32 v[244:245], v[22:23], v[38:39] neg_lo:[0,1] neg_hi:[0,1]
	v_pk_add_f32 v[246:247], v[30:31], v[42:43] op_sel:[0,1] op_sel_hi:[1,0] neg_lo:[0,1]
	ds_write_b128 v125, v[240:243]
	ds_write_b128 v125, v[244:247] offset:16
	s_waitcnt lgkmcnt(0)
	s_barrier
; #define LAS __attribute__((address_space(3)))
; __device__ __forceinline__ cf cconj(cf a) { return (cf){a.x, -a.y}; }
; __device__ __forceinline__ int p_of_k(int k) { return ((k & 15) << 10) | (((k >> 4) & 15) << 6) | (((k >> 8) & 15) << 2) | (k >> 12); }
; __device__ __forceinline__ void hyena_phase(LAS unsigned char* L, const Args& a, int vcu, int G) {
;     ...
;         {
; #pragma unroll
;             for (int i = 0; i < 8; ++i) {
;                 const int g = tid + 512 * i;
;                 const int kg = (g >> 8) | (((g >> 4) & 15) << 4) | ((g & 15) << 8);
;                 const int pp0 = p_of_k((NFFT - kg) & (NFFT - 1)), pp1 = p_of_k(12288 - kg);
;                 const int p0 = PH(4 * g);
;                 const f32x4 zz = *(LAS f32x4*)(z + p0);
;                 const cf zk0 = {zz[0], zz[1]}, zk1 = {zz[2], zz[3]};
;                 const cf zn0 = z[PH(pp0)], zn1 = z[PH(pp1)];
;                 const f32x4 s0 = sd[2 * i], s1 = sd[2 * i + 1];
;                 const cf S0 = {s0[0], s0[1]}, D0 = {s0[2], s0[3]}, S1 = {s1[0], s1[1]}, D1 = {s1[2], s1[3]};
;                 const cf w0 = cmul(zk0, S0) + cmul(cconj(zn0), D0), w1 = cmul(zk1, S1) + cmul(cconj(zn1), D1);
;                 *(LAS f32x4*)(z + p0) = (f32x4){w0.x, w0.y, w1.x, w1.y};
;                 if (kg != 0) z[PH(pp0)] = cmulc(zn0, S0) + cconj(cmul(zk0, D0));
;                 z[PH(pp1)] = cmulc(zn1, S1) + cconj(cmul(zk1, D1));
	ds_read_b128 v[112:115], v186
	ds_read_b64 v[30:31], v187
	ds_read_b64 v[22:23], v188
	s_waitcnt vmcnt(14) lgkmcnt(2)
	v_pk_mul_f32 v[38:39], v[112:113], v[108:109] op_sel:[0,0] op_sel_hi:[0,1]
	s_waitcnt lgkmcnt(1)
	v_pk_add_f32 v[42:43], v[30:31], 0 neg_lo:[1,1] neg_hi:[1,1]
	v_pk_fma_f32 v[38:39], v[112:113], v[108:109], v[38:39] op_sel:[1,1,0] op_sel_hi:[1,0,1] neg_lo:[1,0,0]
	v_mov_b32_e32 v42, v30
	v_pk_mul_f32 v[230:231], v[42:43], v[110:111] op_sel:[0,0] op_sel_hi:[0,1]
	v_pk_fma_f32 v[42:43], v[42:43], v[110:111], v[230:231] op_sel:[1,1,0] op_sel_hi:[1,0,1] neg_lo:[1,0,0]
	v_pk_mul_f32 v[230:231], v[114:115], v[104:105] op_sel:[0,0] op_sel_hi:[0,1]
	v_pk_fma_f32 v[232:233], v[114:115], v[104:105], v[230:231] op_sel:[1,1,0] op_sel_hi:[1,0,1] neg_lo:[1,0,0]
	s_waitcnt lgkmcnt(0)
	v_pk_add_f32 v[230:231], v[22:23], 0 neg_lo:[1,1] neg_hi:[1,1]
	s_nop 0
	v_mov_b32_e32 v230, v22
	v_pk_mul_f32 v[234:235], v[230:231], v[106:107] op_sel:[0,0] op_sel_hi:[0,1]
	v_pk_fma_f32 v[234:235], v[230:231], v[106:107], v[234:235] op_sel:[1,1,0] op_sel_hi:[1,0,1] neg_lo:[1,0,0]
	v_pk_add_f32 v[230:231], v[38:39], v[42:43]
	v_pk_add_f32 v[232:233], v[232:233], v[234:235]
	ds_write_b128 v186, v[230:233]
	s_and_saveexec_b64 s[46:47], s[8:9]
	s_cbranch_execz .LBB0_1033
	v_pk_mul_f32 v[38:39], v[30:31], v[108:109] op_sel:[0,0] op_sel_hi:[0,1] neg_hi:[0,1]
	v_pk_fma_f32 v[30:31], v[30:31], v[108:109], v[38:39] op_sel:[1,1,0] op_sel_hi:[1,0,1]
	v_pk_mul_f32 v[38:39], v[112:113], v[110:111] op_sel:[0,0] op_sel_hi:[0,1]
	v_pk_fma_f32 v[38:39], v[112:113], v[110:111], v[38:39] op_sel:[1,1,0] op_sel_hi:[1,0,1] neg_lo:[1,0,0]
	v_pk_add_f32 v[42:43], v[38:39], 0 neg_lo:[1,1] neg_hi:[1,1]
	s_nop 0
	v_mov_b32_e32 v39, v43
	v_pk_add_f32 v[30:31], v[30:31], v[38:39]
	ds_write_b64 v187, v[30:31]

; #define LAS __attribute__((address_space(3)))
; template <bool INV> __device__ __forceinline__ void fft_pass4(LAS cf* z, int tid) {
; #pragma unroll 2
;     for (int it = 0; it < 8; ++it) {
;         const int g = tid + 512 * it; const int pb = PH(4 * g);
;         f32x4 v0 = *(LAS f32x4*)(z + pb), v1 = *(LAS f32x4*)(z + pb + 2);
;         cf a0 = {v0[0], v0[1]}, a1 = {v0[2], v0[3]}, a2 = {v1[0], v1[1]}, a3 = {v1[2], v1[3]};
;         dft4<INV>(a0, a1, a2, a3);
;         *(LAS f32x4*)(z + pb) = (f32x4){a0.x, a0.y, a1.x, a1.y}; *(LAS f32x4*)(z + pb + 2) = (f32x4){a2.x, a2.y, a3.x, a3.y};
;     }
;     __syncthreads();
; }
; __device__ __forceinline__ void hyena_phase(LAS unsigned char* L, const Args& a, int vcu, int G) {
;     ...
;         fft_pass4<true>(z, tid); fft_pass16<true, 2>(z, Thi, Tlo, tid); fft_pass16<true, 6>(z, Thi, Tlo, tid);
.LBB0_1036:
	v_mov_b32_e32 v22, v160
	v_xor_b32_e32 v22, v22, v176
	v_lshl_add_u32 v182, v22, 3, 0
	v_add_u32_e32 v22, 0x800, v160
	v_xor_b32_e32 v22, v22, v176
	v_lshl_add_u32 v183, v22, 3, 0
	v_add_u32_e32 v22, 0x1000, v160
	v_xor_b32_e32 v22, v22, v176
	v_lshl_add_u32 v216, v22, 3, 0
	v_add_u32_e32 v22, 0x1800, v160
	v_xor_b32_e32 v22, v22, v176
	v_lshl_add_u32 v217, v22, 3, 0
	v_add_u32_e32 v22, 0x2000, v160
	v_xor_b32_e32 v22, v22, v176
	v_lshl_add_u32 v226, v22, 3, 0
	v_add_u32_e32 v22, 0x2800, v160
	v_xor_b32_e32 v22, v22, v176
	v_lshl_add_u32 v227, v22, 3, 0
	v_add_u32_e32 v22, 0x3000, v160
	v_xor_b32_e32 v22, v22, v176
	v_lshl_add_u32 v41, v22, 3, 0
	v_add_u32_e32 v22, 0x3800, v160
	v_xor_b32_e32 v22, v22, v176
	v_lshl_add_u32 v125, v22, 3, 0
	ds_read_b128 v[70:73], v182
	ds_read_b128 v[74:77], v182 offset:16
	ds_read_b128 v[78:81], v183
	ds_read_b128 v[82:85], v183 offset:16
	ds_read_b128 v[86:89], v216
	ds_read_b128 v[90:93], v216 offset:16
	ds_read_b128 v[94:97], v217
	ds_read_b128 v[98:101], v217 offset:16
	ds_read_b128 v[102:105], v226
	ds_read_b128 v[106:109], v226 offset:16
	ds_read_b128 v[110:113], v227
	ds_read_b128 v[236:239], v227 offset:16
	ds_read_b128 v[240:243], v41
	ds_read_b128 v[244:247], v41 offset:16
	ds_read_b128 v[248:251], v125
	ds_read_b128 v[48:51], v125 offset:16
	s_waitcnt lgkmcnt(14)
	v_pk_add_f32 v[22:23], v[70:71], v[74:75]
	v_pk_add_f32 v[38:39], v[72:73], v[76:77]
	v_pk_add_f32 v[30:31], v[70:71], v[74:75] neg_lo:[0,1] neg_hi:[0,1]
	v_pk_add_f32 v[42:43], v[72:73], v[76:77] neg_lo:[0,1] neg_hi:[0,1]
	v_pk_add_f32 v[70:71], v[22:23], v[38:39]
	v_pk_add_f32 v[72:73], v[30:31], v[42:43] op_sel:[0,1] op_sel_hi:[1,0] neg_lo:[0,1]
	v_pk_add_f32 v[74:75], v[22:23], v[38:39] neg_lo:[0,1] neg_hi:[0,1]
	v_pk_add_f32 v[76:77], v[30:31], v[42:43] op_sel:[0,1] op_sel_hi:[1,0] neg_hi:[0,1]
	ds_write_b128 v182, v[70:73]
	ds_write_b128 v182, v[74:77] offset:16
	s_waitcnt lgkmcnt(14)
	v_pk_add_f32 v[22:23], v[78:79], v[82:83]
	v_pk_add_f32 v[38:39], v[80:81], v[84:85]
	v_pk_add_f32 v[30:31], v[78:79], v[82:83] neg_lo:[0,1] neg_hi:[0,1]
	v_pk_add_f32 v[42:43], v[80:81], v[84:85] neg_lo:[0,1] neg_hi:[0,1]
	v_pk_add_f32 v[78:79], v[22:23], v[38:39]
	v_pk_add_f32 v[80:81], v[30:31], v[42:43] op_sel:[0,1] op_sel_hi:[1,0] neg_lo:[0,1]
	v_pk_add_f32 v[82:83], v[22:23], v[38:39] neg_lo:[0,1] neg_hi:[0,1]
	v_pk_add_f32 v[84:85], v[30:31], v[42:43] op_sel:[0,1] op_sel_hi:[1,0] neg_hi:[0,1]
	ds_write_b128 v183, v[78:81]
	ds_write_b128 v183, v[82:85] offset:16
	s_waitcnt lgkmcnt(14)
	v_pk_add_f32 v[22:23], v[86:87], v[90:91]
	v_pk_add_f32 v[38:39], v[88:89], v[92:93]
	v_pk_add_f32 v[30:31], v[86:87], v[90:91] neg_lo:[0,1] neg_hi:[0,1]
	v_pk_add_f32 v[42:43], v[88:89], v[92:93] neg_lo:[0,1] neg_hi:[0,1]
	v_pk_add_f32 v[86:87], v[22:23], v[38:39]
	v_pk_add_f32 v[88:89], v[30:31], v[42:43] op_sel:[0,1] op_sel_hi:[1,0] neg_lo:[0,1]
	v_pk_add_f32 v[90:91], v[22:23], v[38:39] neg_lo:[0,1] neg_hi:[0,1]
	v_pk_add_f32 v[92:93], v[30:31], v[42:43] op_sel:[0,1] op_sel_hi:[1,0] neg_hi:[0,1]
	ds_write_b128 v216, v[86:89]
	ds_write_b128 v216, v[90:93] offset:16
	s_waitcnt lgkmcnt(14)
	v_pk_add_f32 v[22:23], v[94:95], v[98:99]
	v_pk_add_f32 v[38:39], v[96:97], v[100:101]
	v_pk_add_f32 v[30:31], v[94:95], v[98:99] neg_lo:[0,1] neg_hi:[0,1]
	v_pk_add_f32 v[42:43], v[96:97], v[100:101] neg_lo:[0,1] neg_hi:[0,1]
	v_pk_add_f32 v[94:95], v[22:23], v[38:39]
	v_pk_add_f32 v[96:97], v[30:31], v[42:43] op_sel:[0,1] op_sel_hi:[1,0] neg_lo:[0,1]
	v_pk_add_f32 v[98:99], v[22:23], v[38:39] neg_lo:[0,1] neg_hi:[0,1]
	v_pk_add_f32 v[100:101], v[30:31], v[42:43] op_sel:[0,1] op_sel_hi:[1,0] neg_hi:[0,1]
	ds_write_b128 v217, v[94:97]
	ds_write_b128 v217, v[98:101] offset:16
	s_waitcnt lgkmcnt(14)
	v_pk_add_f32 v[22:23], v[102:103], v[106:107]
	v_pk_add_f32 v[38:39], v[104:105], v[108:109]
	v_pk_add_f32 v[30:31], v[102:103], v[106:107] neg_lo:[0,1] neg_hi:[0,1]
	v_pk_add_f32 v[42:43], v[104:105], v[108:109] neg_lo:[0,1] neg_hi:[0,1]
	v_pk_add_f32 v[102:103], v[22:23], v[38:39]
	v_pk_add_f32 v[104:105], v[30:31], v[42:43] op_sel:[0,1] op_sel_hi:[1,0] neg_lo:[0,1]
	v_pk_add_f32 v[106:107], v[22:23], v[38:39] neg_lo:[0,1] neg_hi:[0,1]
	v_pk_add_f32 v[108:109], v[30:31], v[42:43] op_sel:[0,1] op_sel_hi:[1,0] neg_hi:[0,1]
	ds_write_b128 v226, v[102:105]
	ds_write_b128 v226, v[106:109] offset:16
	s_waitcnt lgkmcnt(14)
	v_pk_add_f32 v[22:23], v[110:111], v[236:237]
	v_pk_add_f32 v[38:39], v[112:113], v[238:239]
	v_pk_add_f32 v[30:31], v[110:111], v[236:237] neg_lo:[0,1] neg_hi:[0,1]
	v_pk_add_f32 v[42:43], v[112:113], v[238:239] neg_lo:[0,1] neg_hi:[0,1]
	v_pk_add_f32 v[110:111], v[22:23], v[38:39]
	v_pk_add_f32 v[112:113], v[30:31], v[42:43] op_sel:[0,1] op_sel_hi:[1,0] neg_lo:[0,1]
	v_pk_add_f32 v[236:237], v[22:23], v[38:39] neg_lo:[0,1] neg_hi:[0,1]
	v_pk_add_f32 v[238:239], v[30:31], v[42:43] op_sel:[0,1] op_sel_hi:[1,0] neg_hi:[0,1]
	ds_write_b128 v227, v[110:113]
	ds_write_b128 v227, v[236:239] offset:16
	s_waitcnt lgkmcnt(14)
	v_pk_add_f32 v[22:23], v[240:241], v[244:245]
	v_pk_add_f32 v[38:39], v[242:243], v[246:247]
	v_pk_add_f32 v[30:31], v[240:241], v[244:245] neg_lo:[0,1] neg_hi:[0,1]
	v_pk_add_f32 v[42:43], v[242:243], v[246:247] neg_lo:[0,1] neg_hi:[0,1]
	v_pk_add_f32 v[240:241], v[22:23], v[38:39]
	v_pk_add_f32 v[242:243], v[30:31], v[42:43] op_sel:[0,1] op_sel_hi:[1,0] neg_lo:[0,1]
	v_pk_add_f32 v[244:245], v[22:23], v[38:39] neg_lo:[0,1] neg_hi:[0,1]
	v_pk_add_f32 v[246:247], v[30:31], v[42:43] op_sel:[0,1] op_sel_hi:[1,0] neg_hi:[0,1]
	ds_write_b128 v41, v[240:243]
	ds_write_b128 v41, v[244:247] offset:16
	s_waitcnt lgkmcnt(14)
	v_pk_add_f32 v[22:23], v[248:249], v[48:49]
	v_pk_add_f32 v[38:39], v[250:251], v[50:51]
	v_pk_add_f32 v[30:31], v[248:249], v[48:49] neg_lo:[0,1] neg_hi:[0,1]
	v_pk_add_f32 v[42:43], v[250:251], v[50:51] neg_lo:[0,1] neg_hi:[0,1]
	v_pk_add_f32 v[248:249], v[22:23], v[38:39]
	v_pk_add_f32 v[250:251], v[30:31], v[42:43] op_sel:[0,1] op_sel_hi:[1,0] neg_lo:[0,1]
	v_pk_add_f32 v[48:49], v[22:23], v[38:39] neg_lo:[0,1] neg_hi:[0,1]
	v_pk_add_f32 v[50:51], v[30:31], v[42:43] op_sel:[0,1] op_sel_hi:[1,0] neg_hi:[0,1]
	ds_write_b128 v125, v[248:251]
	ds_write_b128 v125, v[48:51] offset:16
	s_mov_b32 s21, 0
	s_mov_b64 s[44:45], -1
	s_waitcnt lgkmcnt(0)
	s_barrier
	s_branch .LBB0_1039
